# P9 final epilogue: second-half residual loads hoisted into the first half as in P2/P7
# baseline (speedup 1.0000x reference)
;     __device__ __forceinline__ void operator()(f32x4 (&acc)[2][2][4][2], const Unit& u, int wr, int wc, int fr, int fq) const {
;         const int row0 = u.pm * BM + wr * 64 + fr, col0 = u.pn * BM + wc * 32 + 8 * fq;
; #pragma unroll
;         for (int ai = 0; ai < 2; ++ai) {
;         u32x4 xin[4][2];
; #pragma unroll
;             for (int m = 0; m < 4; ++m)
; #pragma unroll
;                 for (int bj = 0; bj < 2; ++bj) xin[m][bj] = *(const u32x4*)(xb + (size_t)(row0 + ai * HALF + m * 16) * DM + col0 + bj * HALF);
; #pragma unroll
;             for (int m = 0; m < 4; ++m) {
;                 const int row = row0 + ai * HALF + m * 16; float q = 0.f;
; #pragma unroll
;                 for (int bj = 0; bj < 2; ++bj) {
;                     f32x4 b0, b1; bf8_to_f32(xin[m][bj], b0, b1);
;                     const f32x4 o0 = b0 + acc[ai][bj][m][0] * scale, o1 = b1 + acc[ai][bj][m][1] * scale;
;                     acc[ai][bj][m][0] = o0; acc[ai][bj][m][1] = o1;
;                     q += ((o0[0] * o0[0] + o0[1] * o0[1]) + (o0[2] * o0[2] + o0[3] * o0[3])) + ((o1[0] * o1[0] + o1[1] * o1[1]) + (o1[2] * o1[2] + o1[3] * o1[3]));
;                 }
;                 q += __shfl_xor(q, 16); q += __shfl_xor(q, 32);
;                 if (fq == 0) __hip_atomic_store((unsigned*)(ss + (size_t)row * 16 + u.pn * 4 + wc), __float_as_uint(q), __ATOMIC_RELAXED, __HIP_MEMORY_SCOPE_AGENT);
;             }
.LBB0_1447:
	s_or_b64 exec, exec, s[10:11]
	v_add_u32_e32 v198, 0x80, v176
	v_ashrrev_i32_e32 v199, 31, v198
	v_lshlrev_b64 v[198:199], 11, v[198:199]
	v_lshl_add_u64 v[198:199], v[192:193], 0, v[198:199]
	global_load_dwordx4 v[194:197], v[198:199], off
	global_load_dwordx4 v[222:225], v[198:199], off offset:256
	v_add_u32_e32 v208, 0x90, v176
	v_ashrrev_i32_e32 v209, 31, v208
	v_lshlrev_b64 v[208:209], 11, v[208:209]
	v_lshl_add_u64 v[208:209], v[192:193], 0, v[208:209]
	global_load_dwordx4 v[226:229], v[208:209], off
	global_load_dwordx4 v[230:233], v[208:209], off offset:256
	v_add_u32_e32 v198, 0xa0, v176
	v_ashrrev_i32_e32 v199, 31, v198
	v_lshlrev_b64 v[198:199], 11, v[198:199]
	v_lshl_add_u64 v[198:199], v[192:193], 0, v[198:199]
	global_load_dwordx4 v[234:237], v[198:199], off
	global_load_dwordx4 v[238:241], v[198:199], off offset:256
	v_add_u32_e32 v208, 0xb0, v176
	v_ashrrev_i32_e32 v209, 31, v208
	v_lshlrev_b64 v[208:209], 11, v[208:209]
	v_lshl_add_u64 v[208:209], v[192:193], 0, v[208:209]
	global_load_dwordx4 v[242:245], v[208:209], off
	global_load_dwordx4 v[246:249], v[208:209], off offset:256
	v_lshlrev_b32_e32 v178, 16, v148
	s_waitcnt lgkmcnt(0)
	v_and_b32_e32 v179, 0xffff0000, v148
	v_lshlrev_b32_e32 v148, 16, v149
	v_and_b32_e32 v149, 0xffff0000, v149
	v_lshlrev_b32_e32 v180, 16, v150
	v_and_b32_e32 v181, 0xffff0000, v150
	v_pk_fma_f32 v[184:185], v[110:111], 0.5, v[148:149] op_sel_hi:[1,0,1]
	v_pk_fma_f32 v[188:189], v[108:109], 0.5, v[178:179] op_sel_hi:[1,0,1]
	v_lshlrev_b32_e32 v150, 16, v151
	v_and_b32_e32 v151, 0xffff0000, v151
	v_pk_fma_f32 v[186:187], v[104:105], 0.5, v[180:181] op_sel_hi:[1,0,1]
	v_mul_f32_e32 v104, v189, v189
	v_mul_f32_e32 v105, v185, v185
	v_pk_fma_f32 v[106:107], v[106:107], 0.5, v[150:151] op_sel_hi:[1,0,1]
	v_fmac_f32_e32 v104, v188, v188
	v_fmac_f32_e32 v105, v184, v184
	v_add_f32_e32 v104, v104, v105
	v_mul_f32_e32 v105, v187, v187
	v_mul_f32_e32 v108, v107, v107
	v_fmac_f32_e32 v105, v186, v186
	v_fmac_f32_e32 v108, v106, v106
	v_add_f32_e32 v105, v105, v108
	v_add_f32_e32 v178, v104, v105
	v_lshlrev_b32_e32 v104, 16, v144
	v_and_b32_e32 v105, 0xffff0000, v144
	v_lshlrev_b32_e32 v108, 16, v145
	v_and_b32_e32 v109, 0xffff0000, v145
	v_lshlrev_b32_e32 v110, 16, v146
	v_and_b32_e32 v111, 0xffff0000, v146
	v_lshlrev_b32_e32 v144, 16, v147
	v_and_b32_e32 v145, 0xffff0000, v147
	v_pk_fma_f32 v[146:147], v[102:103], 0.5, v[108:109] op_sel_hi:[1,0,1]
	v_pk_fma_f32 v[150:151], v[100:101], 0.5, v[104:105] op_sel_hi:[1,0,1]
	v_pk_fma_f32 v[148:149], v[96:97], 0.5, v[110:111] op_sel_hi:[1,0,1]
	v_mul_f32_e32 v96, v151, v151
	v_mul_f32_e32 v97, v147, v147
	v_pk_fma_f32 v[144:145], v[98:99], 0.5, v[144:145] op_sel_hi:[1,0,1]
	v_fmac_f32_e32 v96, v150, v150
	v_fmac_f32_e32 v97, v146, v146
	v_add_f32_e32 v96, v96, v97
	v_mul_f32_e32 v97, v149, v149
	v_mul_f32_e32 v98, v145, v145
	v_fmac_f32_e32 v97, v148, v148
	v_fmac_f32_e32 v98, v144, v144
	v_add_f32_e32 v97, v97, v98
	v_add_f32_e32 v96, v96, v97
	v_add_f32_e32 v96, v178, v96
	ds_bpermute_b32 v97, v219, v96
	v_lshlrev_b64 v[202:203], 6, v[174:175]
	s_waitcnt lgkmcnt(0)
	v_add_f32_e32 v96, v96, v97
	ds_bpermute_b32 v97, v220, v96
	s_and_saveexec_b64 s[10:11], s[0:1]
	s_cbranch_execz .LBB0_1449
	s_waitcnt lgkmcnt(0)
	v_add_f32_e32 v98, v96, v97
	v_lshl_add_u64 v[96:97], s[16:17], 0, v[202:203]
	v_lshl_add_u64 v[96:97], s[6:7], 2, v[96:97]
	s_lshl_b32 s12, s36, 2
	v_lshl_add_u64 v[96:97], v[96:97], 0, s[12:13]
	global_store_dword v[96:97], v98, off sc1

;     __device__ __forceinline__ void operator()(f32x4 (&acc)[2][2][4][2], const Unit& u, int wr, int wc, int fr, int fq) const {
;     ...
;         for (int ai = 0; ai < 2; ++ai) {
;         u32x4 xin[4][2];
; #pragma unroll
;             for (int m = 0; m < 4; ++m)
; #pragma unroll
;                 for (int bj = 0; bj < 2; ++bj) xin[m][bj] = *(const u32x4*)(xb + (size_t)(row0 + ai * HALF + m * 16) * DM + col0 + bj * HALF);
; #pragma unroll
;             for (int m = 0; m < 4; ++m) {
;                 const int row = row0 + ai * HALF + m * 16; float q = 0.f;
; #pragma unroll
;                 for (int bj = 0; bj < 2; ++bj) {
;                     f32x4 b0, b1; bf8_to_f32(xin[m][bj], b0, b1);
;                     const f32x4 o0 = b0 + acc[ai][bj][m][0] * scale, o1 = b1 + acc[ai][bj][m][1] * scale;
;                     acc[ai][bj][m][0] = o0; acc[ai][bj][m][1] = o1;
;                     q += ((o0[0] * o0[0] + o0[1] * o0[1]) + (o0[2] * o0[2] + o0[3] * o0[3])) + ((o1[0] * o1[0] + o1[1] * o1[1]) + (o1[2] * o1[2] + o1[3] * o1[3]));
;                 }
;                 q += __shfl_xor(q, 16); q += __shfl_xor(q, 32);
;                 if (fq == 0) __hip_atomic_store((unsigned*)(ss + (size_t)row * 16 + u.pn * 4 + wc), __float_as_uint(q), __ATOMIC_RELAXED, __HIP_MEMORY_SCOPE_AGENT);
;             }
.LBB0_1453:
	s_or_b64 exec, exec, s[10:11]
	v_add_u32_e32 v100, 0x80, v176
	v_ashrrev_i32_e32 v101, 31, v100
	s_waitcnt lgkmcnt(0)
	v_lshlrev_b64 v[64:65], 11, v[100:101]
	v_lshl_add_u64 v[64:65], v[192:193], 0, v[64:65]
	s_waitcnt vmcnt(2)
	v_mov_b64_e32 v[128:129], v[194:195]
	v_mov_b64_e32 v[130:131], v[196:197]
	v_mov_b64_e32 v[194:195], v[222:223]
	v_mov_b64_e32 v[196:197], v[224:225]
	v_add_u32_e32 v92, 0x90, v176
	v_add_u32_e32 v90, 0xa0, v176
	v_add_u32_e32 v88, 0xb0, v176
	v_ashrrev_i32_e32 v93, 31, v92
	v_ashrrev_i32_e32 v91, 31, v90
	v_ashrrev_i32_e32 v89, 31, v88
	v_lshlrev_b64 v[64:65], 11, v[92:93]
	v_lshlrev_b64 v[66:67], 11, v[90:91]
	v_lshlrev_b64 v[68:69], 11, v[88:89]
	v_lshl_add_u64 v[64:65], v[192:193], 0, v[64:65]
	v_lshl_add_u64 v[66:67], v[192:193], 0, v[66:67]
	v_lshl_add_u64 v[192:193], v[192:193], 0, v[68:69]
	v_mov_b64_e32 v[84:85], v[226:227]
	v_mov_b64_e32 v[86:87], v[228:229]
	v_mov_b64_e32 v[80:81], v[230:231]
	v_mov_b64_e32 v[82:83], v[232:233]
	v_mov_b64_e32 v[76:77], v[234:235]
	v_mov_b64_e32 v[78:79], v[236:237]
	v_mov_b64_e32 v[72:73], v[238:239]
	v_mov_b64_e32 v[74:75], v[240:241]
	v_mov_b64_e32 v[68:69], v[242:243]
	v_mov_b64_e32 v[70:71], v[244:245]
	s_nop 0
	v_mov_b64_e32 v[64:65], v[246:247]
	v_mov_b64_e32 v[66:67], v[248:249]
	v_lshlrev_b32_e32 v192, 16, v128
	v_and_b32_e32 v193, 0xffff0000, v128
	v_lshlrev_b32_e32 v128, 16, v129
	v_and_b32_e32 v129, 0xffff0000, v129
	v_lshlrev_b32_e32 v208, 16, v130
	v_and_b32_e32 v209, 0xffff0000, v130
	v_lshlrev_b32_e32 v130, 16, v131
	v_and_b32_e32 v131, 0xffff0000, v131
	v_lshlrev_b32_e32 v222, 16, v194
	v_and_b32_e32 v223, 0xffff0000, v194
	v_lshlrev_b32_e32 v224, 16, v195
	v_and_b32_e32 v225, 0xffff0000, v195
	v_lshlrev_b32_e32 v226, 16, v196
	v_and_b32_e32 v227, 0xffff0000, v196
	v_lshlrev_b32_e32 v228, 16, v197
	v_and_b32_e32 v229, 0xffff0000, v197
	v_pk_fma_f32 v[196:197], v[62:63], 0.5, v[128:129] op_sel_hi:[1,0,1]
	v_pk_fma_f32 v[198:199], v[60:61], 0.5, v[192:193] op_sel_hi:[1,0,1]
	v_pk_fma_f32 v[58:59], v[58:59], 0.5, v[130:131] op_sel_hi:[1,0,1]
	v_pk_fma_f32 v[194:195], v[56:57], 0.5, v[208:209] op_sel_hi:[1,0,1]
	v_pk_fma_f32 v[54:55], v[54:55], 0.5, v[224:225] op_sel_hi:[1,0,1]
	v_pk_fma_f32 v[52:53], v[52:53], 0.5, v[222:223] op_sel_hi:[1,0,1]
	v_pk_fma_f32 v[50:51], v[50:51], 0.5, v[228:229] op_sel_hi:[1,0,1]
	v_pk_fma_f32 v[48:49], v[48:49], 0.5, v[226:227] op_sel_hi:[1,0,1]
	v_mul_f32_e32 v56, v199, v199
	v_mul_f32_e32 v57, v197, v197
	v_mul_f32_e32 v60, v195, v195
	v_mul_f32_e32 v61, v59, v59
	v_mul_f32_e32 v62, v53, v53
	v_mul_f32_e32 v63, v55, v55
	v_mul_f32_e32 v128, v49, v49
	v_mul_f32_e32 v129, v51, v51
	v_fmac_f32_e32 v56, v198, v198
	v_fmac_f32_e32 v57, v196, v196
	v_fmac_f32_e32 v60, v194, v194
	v_fmac_f32_e32 v61, v58, v58
	v_fmac_f32_e32 v62, v52, v52
	v_fmac_f32_e32 v63, v54, v54
	v_fmac_f32_e32 v128, v48, v48
	v_fmac_f32_e32 v129, v50, v50
	v_add_f32_e32 v56, v56, v57
	v_add_f32_e32 v57, v60, v61
	v_add_f32_e32 v60, v62, v63
	v_add_f32_e32 v61, v128, v129
	v_add_f32_e32 v56, v56, v57
	v_add_f32_e32 v57, v60, v61
	v_add_f32_e32 v56, v56, v57
	ds_bpermute_b32 v57, v219, v56
	v_lshlrev_b64 v[208:209], 6, v[100:101]
	s_waitcnt lgkmcnt(0)
	v_add_f32_e32 v56, v56, v57
	ds_bpermute_b32 v57, v220, v56
	s_and_saveexec_b64 s[10:11], s[0:1]
	s_cbranch_execz .LBB0_1455
	s_waitcnt lgkmcnt(0)
	v_add_f32_e32 v60, v56, v57
	v_lshl_add_u64 v[56:57], s[16:17], 0, v[208:209]
	v_lshl_add_u64 v[56:57], s[6:7], 2, v[56:57]
	s_lshl_b32 s12, s36, 2
	v_lshl_add_u64 v[56:57], v[56:57], 0, s[12:13]
	global_store_dword v[56:57], v60, off sc1
.LBB0_1455:
	s_or_b64 exec, exec, s[10:11]
	v_lshlrev_b32_e32 v56, 16, v84
	s_waitcnt lgkmcnt(0)
	v_and_b32_e32 v57, 0xffff0000, v84
	v_lshlrev_b32_e32 v60, 16, v85
	v_and_b32_e32 v61, 0xffff0000, v85
	v_lshlrev_b32_e32 v62, 16, v86
	v_and_b32_e32 v63, 0xffff0000, v86
	v_lshlrev_b32_e32 v86, 16, v87
	v_and_b32_e32 v87, 0xffff0000, v87
	v_pk_fma_f32 v[84:85], v[46:47], 0.5, v[60:61] op_sel_hi:[1,0,1]
	v_pk_fma_f32 v[192:193], v[44:45], 0.5, v[56:57] op_sel_hi:[1,0,1]
	v_pk_fma_f32 v[42:43], v[42:43], 0.5, v[86:87] op_sel_hi:[1,0,1]
	v_pk_fma_f32 v[86:87], v[40:41], 0.5, v[62:63] op_sel_hi:[1,0,1]
	v_mul_f32_e32 v40, v193, v193
	v_mul_f32_e32 v41, v85, v85
	v_fmac_f32_e32 v40, v192, v192
	v_fmac_f32_e32 v41, v84, v84
	v_add_f32_e32 v40, v40, v41
	v_mul_f32_e32 v41, v87, v87
	v_mul_f32_e32 v44, v43, v43
	v_fmac_f32_e32 v41, v86, v86
	v_fmac_f32_e32 v44, v42, v42
	v_add_f32_e32 v41, v41, v44
	v_add_f32_e32 v128, v40, v41
	v_lshlrev_b32_e32 v40, 16, v80
	v_and_b32_e32 v41, 0xffff0000, v80
	v_lshlrev_b32_e32 v44, 16, v81
	v_and_b32_e32 v45, 0xffff0000, v81
	v_lshlrev_b32_e32 v56, 16, v82
	v_and_b32_e32 v57, 0xffff0000, v82
	v_pk_fma_f32 v[60:61], v[38:39], 0.5, v[44:45] op_sel_hi:[1,0,1]
	v_pk_fma_f32 v[80:81], v[36:37], 0.5, v[40:41] op_sel_hi:[1,0,1]
	v_lshlrev_b32_e32 v46, 16, v83
	v_and_b32_e32 v47, 0xffff0000, v83
	v_pk_fma_f32 v[62:63], v[32:33], 0.5, v[56:57] op_sel_hi:[1,0,1]
	v_mul_f32_e32 v32, v81, v81
	v_mul_f32_e32 v33, v61, v61
	v_pk_fma_f32 v[46:47], v[34:35], 0.5, v[46:47] op_sel_hi:[1,0,1]
	v_fmac_f32_e32 v32, v80, v80
	v_fmac_f32_e32 v33, v60, v60
	v_add_f32_e32 v32, v32, v33
	v_mul_f32_e32 v33, v63, v63
	v_mul_f32_e32 v34, v47, v47
	v_fmac_f32_e32 v33, v62, v62
	v_fmac_f32_e32 v34, v46, v46
	v_add_f32_e32 v33, v33, v34
	v_add_f32_e32 v32, v32, v33
	v_add_f32_e32 v32, v128, v32
	ds_bpermute_b32 v33, v219, v32
	s_waitcnt lgkmcnt(0)
	v_add_f32_e32 v34, v32, v33
	ds_bpermute_b32 v35, v220, v34
	v_lshlrev_b64 v[32:33], 6, v[92:93]
	s_and_saveexec_b64 s[10:11], s[0:1]
	s_cbranch_execz .LBB0_1457
	s_waitcnt lgkmcnt(0)
	v_add_f32_e32 v36, v34, v35
	v_lshl_add_u64 v[34:35], s[16:17], 0, v[32:33]
	v_lshl_add_u64 v[34:35], s[6:7], 2, v[34:35]
	s_lshl_b32 s12, s36, 2
	v_lshl_add_u64 v[34:35], v[34:35], 0, s[12:13]
	global_store_dword v[34:35], v36, off sc1
;     __device__ __forceinline__ void operator()(f32x4 (&acc)[2][2][4][2], const Unit& u, int wr, int wc, int fr, int fq) const {
;     ...
;             for (int m = 0; m < 4; ++m) {
;                 const int row = row0 + ai * HALF + m * 16; float q = 0.f;
; #pragma unroll
;                 for (int bj = 0; bj < 2; ++bj) {
;                     f32x4 b0, b1; bf8_to_f32(xin[m][bj], b0, b1);
;                     const f32x4 o0 = b0 + acc[ai][bj][m][0] * scale, o1 = b1 + acc[ai][bj][m][1] * scale;
;                     acc[ai][bj][m][0] = o0; acc[ai][bj][m][1] = o1;
;                     q += ((o0[0] * o0[0] + o0[1] * o0[1]) + (o0[2] * o0[2] + o0[3] * o0[3])) + ((o1[0] * o1[0] + o1[1] * o1[1]) + (o1[2] * o1[2] + o1[3] * o1[3]));
;                 }
;                 q += __shfl_xor(q, 16); q += __shfl_xor(q, 32);
;                 if (fq == 0) __hip_atomic_store((unsigned*)(ss + (size_t)row * 16 + u.pn * 4 + wc), __float_as_uint(q), __ATOMIC_RELAXED, __HIP_MEMORY_SCOPE_AGENT);
;             }
.LBB0_1457:
	s_or_b64 exec, exec, s[10:11]
	v_lshlrev_b32_e32 v34, 16, v76
	s_waitcnt lgkmcnt(0)
	v_and_b32_e32 v35, 0xffff0000, v76
	v_lshlrev_b32_e32 v36, 16, v77
	v_and_b32_e32 v37, 0xffff0000, v77
	v_lshlrev_b32_e32 v38, 16, v78
	v_and_b32_e32 v39, 0xffff0000, v78
	v_pk_fma_f32 v[76:77], v[30:31], 0.5, v[36:37] op_sel_hi:[1,0,1]
	v_pk_fma_f32 v[82:83], v[28:29], 0.5, v[34:35] op_sel_hi:[1,0,1]
	v_lshlrev_b32_e32 v40, 16, v79
	v_and_b32_e32 v41, 0xffff0000, v79
	v_pk_fma_f32 v[78:79], v[24:25], 0.5, v[38:39] op_sel_hi:[1,0,1]
	v_mul_f32_e32 v24, v83, v83
	v_mul_f32_e32 v25, v77, v77
	v_pk_fma_f32 v[36:37], v[26:27], 0.5, v[40:41] op_sel_hi:[1,0,1]
	v_fmac_f32_e32 v24, v82, v82
	v_fmac_f32_e32 v25, v76, v76
	v_add_f32_e32 v24, v24, v25
	v_mul_f32_e32 v25, v79, v79
	v_mul_f32_e32 v26, v37, v37
	v_fmac_f32_e32 v25, v78, v78
	v_fmac_f32_e32 v26, v36, v36
	v_add_f32_e32 v25, v25, v26
	v_add_f32_e32 v34, v24, v25
	v_lshlrev_b32_e32 v24, 16, v72
	v_and_b32_e32 v25, 0xffff0000, v72
	v_lshlrev_b32_e32 v26, 16, v73
	v_and_b32_e32 v27, 0xffff0000, v73
	v_lshlrev_b32_e32 v28, 16, v74
	v_and_b32_e32 v29, 0xffff0000, v74
	v_pk_fma_f32 v[40:41], v[22:23], 0.5, v[26:27] op_sel_hi:[1,0,1]
	v_pk_fma_f32 v[56:57], v[20:21], 0.5, v[24:25] op_sel_hi:[1,0,1]
	v_lshlrev_b32_e32 v30, 16, v75
	v_and_b32_e32 v31, 0xffff0000, v75
	v_pk_fma_f32 v[44:45], v[16:17], 0.5, v[28:29] op_sel_hi:[1,0,1]
	v_mul_f32_e32 v16, v57, v57
	v_mul_f32_e32 v17, v41, v41
	v_pk_fma_f32 v[38:39], v[18:19], 0.5, v[30:31] op_sel_hi:[1,0,1]
	v_fmac_f32_e32 v16, v56, v56
	v_fmac_f32_e32 v17, v40, v40
	v_add_f32_e32 v16, v16, v17
	v_mul_f32_e32 v17, v45, v45
	v_mul_f32_e32 v18, v39, v39
	v_fmac_f32_e32 v17, v44, v44
	v_fmac_f32_e32 v18, v38, v38
	v_add_f32_e32 v17, v17, v18
	v_add_f32_e32 v16, v16, v17
	v_add_f32_e32 v16, v34, v16
	ds_bpermute_b32 v17, v219, v16
	s_waitcnt lgkmcnt(0)
	v_add_f32_e32 v18, v16, v17
	ds_bpermute_b32 v19, v220, v18
	v_lshlrev_b64 v[16:17], 6, v[90:91]
	s_and_saveexec_b64 s[10:11], s[0:1]
	s_cbranch_execz .LBB0_1459
	s_waitcnt lgkmcnt(0)
	v_add_f32_e32 v20, v18, v19
	v_lshl_add_u64 v[18:19], s[16:17], 0, v[16:17]
	v_lshl_add_u64 v[18:19], s[6:7], 2, v[18:19]
	s_lshl_b32 s12, s36, 2
	v_lshl_add_u64 v[18:19], v[18:19], 0, s[12:13]
	global_store_dword v[18:19], v20, off sc1
.LBB0_1459:
	s_or_b64 exec, exec, s[10:11]
	v_lshlrev_b32_e32 v18, 16, v68
	s_waitcnt lgkmcnt(0)
	v_and_b32_e32 v19, 0xffff0000, v68
	v_lshlrev_b32_e32 v20, 16, v69
	v_and_b32_e32 v21, 0xffff0000, v69
	v_lshlrev_b32_e32 v22, 16, v70
	v_and_b32_e32 v23, 0xffff0000, v70
	v_lshlrev_b32_e32 v24, 16, v71
	v_and_b32_e32 v25, 0xffff0000, v71
	v_pk_fma_f32 v[70:71], v[14:15], 0.5, v[20:21] op_sel_hi:[1,0,1]
	v_pk_fma_f32 v[74:75], v[12:13], 0.5, v[18:19] op_sel_hi:[1,0,1]
	v_pk_fma_f32 v[72:73], v[8:9], 0.5, v[22:23] op_sel_hi:[1,0,1]
	v_mul_f32_e32 v8, v75, v75
	v_mul_f32_e32 v9, v71, v71
	v_pk_fma_f32 v[68:69], v[10:11], 0.5, v[24:25] op_sel_hi:[1,0,1]
	v_fmac_f32_e32 v8, v74, v74
	v_fmac_f32_e32 v9, v70, v70
	v_add_f32_e32 v8, v8, v9
	v_mul_f32_e32 v9, v73, v73
	v_mul_f32_e32 v10, v69, v69
	v_fmac_f32_e32 v9, v72, v72
	v_fmac_f32_e32 v10, v68, v68
	v_add_f32_e32 v9, v9, v10
	v_add_f32_e32 v18, v8, v9
	v_lshlrev_b32_e32 v8, 16, v64
	v_and_b32_e32 v9, 0xffff0000, v64
	v_lshlrev_b32_e32 v10, 16, v65
	v_and_b32_e32 v11, 0xffff0000, v65
	v_lshlrev_b32_e32 v12, 16, v66
	v_and_b32_e32 v13, 0xffff0000, v66
	v_lshlrev_b32_e32 v14, 16, v67
	v_and_b32_e32 v15, 0xffff0000, v67
	v_pk_fma_f32 v[66:67], v[6:7], 0.5, v[10:11] op_sel_hi:[1,0,1]
	v_pk_fma_f32 v[130:131], v[4:5], 0.5, v[8:9] op_sel_hi:[1,0,1]
	v_pk_fma_f32 v[128:129], v[0:1], 0.5, v[12:13] op_sel_hi:[1,0,1]
	v_mul_f32_e32 v0, v131, v131
	v_mul_f32_e32 v1, v67, v67
	v_pk_fma_f32 v[64:65], v[2:3], 0.5, v[14:15] op_sel_hi:[1,0,1]
	v_fmac_f32_e32 v0, v130, v130
	v_fmac_f32_e32 v1, v66, v66
	v_add_f32_e32 v0, v0, v1
	v_mul_f32_e32 v1, v129, v129
	v_mul_f32_e32 v2, v65, v65
	v_fmac_f32_e32 v1, v128, v128
	v_fmac_f32_e32 v2, v64, v64
	v_add_f32_e32 v1, v1, v2
	v_add_f32_e32 v0, v0, v1
	v_add_f32_e32 v0, v18, v0
	ds_bpermute_b32 v1, v219, v0
	s_waitcnt lgkmcnt(0)
	v_add_f32_e32 v2, v0, v1
	ds_bpermute_b32 v3, v220, v2
	v_lshlrev_b64 v[0:1], 6, v[88:89]
	s_and_saveexec_b64 s[10:11], s[0:1]
	s_cbranch_execz .LBB0_1461
	s_waitcnt lgkmcnt(0)
	v_add_f32_e32 v4, v2, v3
	v_lshl_add_u64 v[2:3], s[16:17], 0, v[0:1]
	v_lshl_add_u64 v[2:3], s[6:7], 2, v[2:3]
	s_lshl_b32 s12, s36, 2
	v_lshl_add_u64 v[2:3], v[2:3], 0, s[12:13]
	global_store_dword v[2:3], v4, off sc1
